# fast path: next-tile loads via SGPR base + 32-bit lane offsets (12 VALU instead of 34 incl. 64-bit ops), the two row-max chains interleaved, 2 fewer movs
# speedup vs baseline: 1.0422x; 1.0050x over previous
; DI void attn_item(const Params& p, int l, int item, char* lds) {
;     ...
;   auto gload = [&](int j) {
;     const bf16_t* kb; size_t kld; const bf16_t* vb; size_t vld;
;     if (!samp) { kb = p.z + (size_t)(b * 4096 + j * 64) * NZ + C_K + h * 128; kld = NZ; vb = p.vtp + (size_t)((b * 4 + h) * 128) * 4096 + j * 64; vld = 4096; }
;     else if (j < 16) { kb = p.kc + (size_t)(b * 1024 + j * 64) * 512 + h * 128; kld = 512; vb = p.vct + (size_t)((b * 4 + h) * 128) * 1024 + j * 64; vld = 1024; }
;     else { kb = p.z + (size_t)(MP + b * 64) * NZ + C_K + h * 128; kld = NZ; vb = p.vts + (size_t)((b * 4 + h) * 128) * 64; vld = 64; }
; #pragma unroll
;     for (int i = 0; i < 4; ++i) {
;       const int c = tid + 256 * i;
;       const int mm = c >> 9, key = (c >> 3) & 63, d8 = (c & 7) * 8;
;       rk[i] = *(const u32x4*)(kb + (size_t)key * kld + mm * 64 + d8);
;       const int vd = c >> 3, k8 = (c & 7) * 8;
;       rv[i] = *(const u32x4*)(vb + (size_t)vd * vld + k8);
;     }
;   };
;     ...
;     float mx = -1e30f;
;     const float dbase = qposf - (float)(j * 64 + 4 * hh);
; #pragma unroll
;     for (int kt = 0; kt < 2; ++kt)
; #pragma unroll
;       for (int e = 0; e < 16; ++e) {
;         const float dd = dbase - (float)(kt * 32 + (e & 3) + 8 * (e >> 2));
;         const float v = s[kt][e] * c1 - sl2 * fabsf(dd);
;         s[kt][e] = v; mx = fmaxf(mx, v);
;       }
;     mx = fmaxf(mx, __shfl_xor(mx, 32));
;     const float mnew = fmaxf(mrun, mx);
;     const float alpha = __builtin_amdgcn_exp2f(mrun - mnew);
;     const bool resc = mnew > mrun;
;     mrun = mnew;
.LBB0_599:
	s_lshl_b32 s2, s2, 1
	s_lshl_b32 s3, vcc_lo, 1
	v_mad_u32_u24 v0, s2, v192, v172
	v_mad_u32_u24 v2, s3, v167, v172
	v_lshl_add_u32 v0, v170, 1, v0
	global_load_dwordx4 v[128:131], v0, s[42:43]
	global_load_dwordx4 v[132:135], v2, s[46:47]
	v_mad_u32_u24 v3, s2, v194, v172
	v_mad_u32_u24 v14, s3, v193, v172
	v_lshl_add_u32 v3, v174, 1, v3
	global_load_dwordx4 v[136:139], v3, s[42:43]
	global_load_dwordx4 v[140:143], v14, s[46:47]
	v_mad_u32_u24 v0, s2, v196, v172
	v_mad_u32_u24 v2, s3, v195, v172
	v_lshl_add_u32 v0, v176, 1, v0
	global_load_dwordx4 v[144:147], v0, s[42:43]
	global_load_dwordx4 v[148:151], v2, s[46:47]
	v_mad_u32_u24 v3, s2, v198, v172
	v_mad_u32_u24 v14, s3, v197, v172
	v_lshl_add_u32 v3, v178, 1, v3
	global_load_dwordx4 v[152:155], v3, s[42:43]
	global_load_dwordx4 v[156:159], v14, s[46:47]
	s_branch .Lfa_body
.Lfa_body:
	ds_read_b128 v[2:5], v202
	ds_read_b128 v[6:9], v202 offset:32
	ds_read_b128 v[10:13], v202 offset:64
	ds_read_b128 v[222:225], v202 offset:96
	ds_read_b128 v[226:229], v202 offset:4608
	v_mfma_f32_32x32x8_bf16 v[96:111], v[206:207], v[214:215], 0
	v_mfma_f32_32x32x8_bf16 v[80:95], v[206:207], v[216:217], 0
	s_waitcnt lgkmcnt(4)
	v_mfma_f32_32x32x16_bf16 v[96:111], v[2:5], v[120:123], v[96:111]
	ds_read_b128 v[2:5], v202 offset:4640
	s_waitcnt lgkmcnt(4)
	v_mfma_f32_32x32x16_bf16 v[96:111], v[6:9], v[112:115], v[96:111]
	ds_read_b128 v[6:9], v202 offset:4672
	s_waitcnt lgkmcnt(4)
	v_mfma_f32_32x32x16_bf16 v[96:111], v[10:13], v[116:119], v[96:111]
	ds_read_b128 v[10:13], v202 offset:4704
	s_waitcnt lgkmcnt(4)
	v_mfma_f32_32x32x16_bf16 v[96:111], v[222:225], v[124:127], v[96:111]
	s_waitcnt lgkmcnt(3)
	v_mfma_f32_32x32x16_bf16 v[80:95], v[226:229], v[120:123], v[80:95]
	s_waitcnt lgkmcnt(2)
	v_mfma_f32_32x32x16_bf16 v[80:95], v[2:5], v[112:115], v[80:95]
	s_waitcnt lgkmcnt(1)
	v_mfma_f32_32x32x16_bf16 v[80:95], v[6:9], v[116:119], v[80:95]
	s_waitcnt lgkmcnt(0)
	v_mfma_f32_32x32x16_bf16 v[80:95], v[10:13], v[124:127], v[80:95]
	v_add_u32_e32 v161, 0x4800, v201
	v_add_u32_e32 v173, 0x5800, v201
	v_add_u32_e32 v188, 0x6800, v201
	v_add_u32_e32 v208, 0x7800, v201
	ds_read2_b64 v[222:225], v208 offset0:192 offset1:194
	ds_read2_b64 v[226:229], v161 offset0:4 offset1:6
	s_lshl_b32 s2, s93, 6
	s_sub_i32 s2, s2, 64
	v_cvt_f32_u32_e32 v14, s2
	v_sub_f32_e32 v14, v187, v14
	v_mul_f32_e32 v14, v189, v14
	ds_read2_b64 v[2:5], v161 offset1:2
	ds_read2_b64 v[6:9], v173 offset0:64 offset1:66
	ds_read2_b64 v[10:13], v188 offset0:128 offset1:130
	v_max3_f32 v0, v96, v97, v98
	v_max3_f32 v15, v80, v81, v82
	v_max3_f32 v0, v0, v99, v100
	v_max3_f32 v15, v15, v83, v84
	v_max3_f32 v0, v0, v101, v102
	v_max3_f32 v15, v15, v85, v86
	v_max3_f32 v0, v0, v103, v104
	v_max3_f32 v15, v15, v87, v88
	v_max3_f32 v0, v0, v105, v106
	v_max3_f32 v15, v15, v89, v90
	v_max3_f32 v0, v0, v107, v108
	v_max3_f32 v15, v15, v91, v92
	v_max3_f32 v0, v0, v109, v110
	v_max3_f32 v15, v15, v93, v94
	v_max_f32_e32 v0, v0, v111
	v_max_f32_e32 v15, v15, v95
	v_max_f32_e32 v0, v0, v15
	v_mov_b32_e32 v15, v0
	s_nop 1
	v_permlane32_swap_b32_e32 v15, v0
	s_nop 1
	v_max_f32_e32 v0, v0, v15
	v_fma_f32 v0, v0, s35, -v14
	v_sub_f32_e32 v15, v0, v204
	v_cmp_lt_f32_e32 vcc, 0x41000000, v15
	s_nop 1
	v_cndmask_b32_e32 v15, v204, v0, vcc
	v_sub_f32_e32 v0, v204, v15
	v_exp_f32_e32 v0, v0
	v_mov_b32_e32 v204, v15
	v_add_f32_e32 v14, v15, v14
	s_cbranch_vccz .Lfa_keep
	v_pk_mul_f32 v[78:79], v[78:79], v[0:1] op_sel_hi:[1,0]
	v_pk_mul_f32 v[76:77], v[76:77], v[0:1] op_sel_hi:[1,0]
	v_pk_mul_f32 v[74:75], v[74:75], v[0:1] op_sel_hi:[1,0]
	v_pk_mul_f32 v[72:73], v[72:73], v[0:1] op_sel_hi:[1,0]
	v_pk_mul_f32 v[70:71], v[70:71], v[0:1] op_sel_hi:[1,0]
	v_pk_mul_f32 v[68:69], v[68:69], v[0:1] op_sel_hi:[1,0]
	v_pk_mul_f32 v[66:67], v[66:67], v[0:1] op_sel_hi:[1,0]
	v_pk_mul_f32 v[64:65], v[64:65], v[0:1] op_sel_hi:[1,0]
	v_pk_mul_f32 v[62:63], v[62:63], v[0:1] op_sel_hi:[1,0]
	v_pk_mul_f32 v[60:61], v[60:61], v[0:1] op_sel_hi:[1,0]
	v_pk_mul_f32 v[58:59], v[58:59], v[0:1] op_sel_hi:[1,0]
	v_pk_mul_f32 v[56:57], v[56:57], v[0:1] op_sel_hi:[1,0]
	v_pk_mul_f32 v[54:55], v[54:55], v[0:1] op_sel_hi:[1,0]
	v_pk_mul_f32 v[52:53], v[52:53], v[0:1] op_sel_hi:[1,0]
	v_pk_mul_f32 v[50:51], v[50:51], v[0:1] op_sel_hi:[1,0]
	v_pk_mul_f32 v[48:49], v[48:49], v[0:1] op_sel_hi:[1,0]
	v_pk_mul_f32 v[46:47], v[46:47], v[0:1] op_sel_hi:[1,0]
	v_pk_mul_f32 v[44:45], v[44:45], v[0:1] op_sel_hi:[1,0]
	v_pk_mul_f32 v[42:43], v[42:43], v[0:1] op_sel_hi:[1,0]
	v_pk_mul_f32 v[40:41], v[40:41], v[0:1] op_sel_hi:[1,0]
	v_pk_mul_f32 v[38:39], v[38:39], v[0:1] op_sel_hi:[1,0]
	v_pk_mul_f32 v[36:37], v[36:37], v[0:1] op_sel_hi:[1,0]
	v_pk_mul_f32 v[34:35], v[34:35], v[0:1] op_sel_hi:[1,0]
	v_pk_mul_f32 v[32:33], v[32:33], v[0:1] op_sel_hi:[1,0]
	v_pk_mul_f32 v[30:31], v[30:31], v[0:1] op_sel_hi:[1,0]
	v_pk_mul_f32 v[28:29], v[28:29], v[0:1] op_sel_hi:[1,0]
	v_pk_mul_f32 v[26:27], v[26:27], v[0:1] op_sel_hi:[1,0]
	v_pk_mul_f32 v[24:25], v[24:25], v[0:1] op_sel_hi:[1,0]
	v_pk_mul_f32 v[22:23], v[22:23], v[0:1] op_sel_hi:[1,0]
	v_pk_mul_f32 v[20:21], v[20:21], v[0:1] op_sel_hi:[1,0]
	v_pk_mul_f32 v[18:19], v[18:19], v[0:1] op_sel_hi:[1,0]
	v_pk_mul_f32 v[16:17], v[16:17], v[0:1] op_sel_hi:[1,0]
; DI unsigned pk2(float a, float b) { f32x2 v = {a, b}; bfv2 r = __builtin_convertvector(v, bfv2); return __builtin_bit_cast(unsigned, r); }
; DI void attn_item(const Params& p, int l, int item, char* lds) {
;     ...
; #pragma unroll
;     for (int kt = 0; kt < 2; ++kt)
; #pragma unroll
;       for (int e = 0; e < 16; ++e) { const float pe = __builtin_amdgcn_exp2f(s[kt][e] - mnew); s[kt][e] = pe; ps += pe; }
;     lrun = lrun * alpha + ps;
;     if (__any(resc)) {
; #pragma unroll
;       for (int i = 0; i < 4; ++i)
; #pragma unroll
;         for (int e = 0; e < 16; ++e) O[i][e] *= alpha;
;     }
; #pragma unroll
;     for (int kt = 0; kt < 2; ++kt)
; #pragma unroll
;       for (int sx = 0; sx < 2; ++sx) {
;         u32x4 pb;
;         pb[0] = pk2(s[kt][8 * sx + 0], s[kt][8 * sx + 1]); pb[1] = pk2(s[kt][8 * sx + 2], s[kt][8 * sx + 3]);
;         pb[2] = pk2(s[kt][8 * sx + 4], s[kt][8 * sx + 5]); pb[3] = pk2(s[kt][8 * sx + 6], s[kt][8 * sx + 7]);
;         const bf16x8 pf = __builtin_bit_cast(bf16x8, pb);
; #pragma unroll
;         for (int vt = 0; vt < 4; ++vt) {
;           const bf16_t* vp = Vs + (vt * 32 + q) * ALD + kt * 32 + 16 * sx + 4 * hh;
;           const s16x4 lo = *(const s16x4*)vp, hi = *(const s16x4*)(vp + 8);
;           const bf16x8 vf = __builtin_shufflevector(lo, hi, 0, 1, 2, 3, 4, 5, 6, 7);
;           O[vt] = __builtin_amdgcn_mfma_f32_32x32x16_bf16(vf, pf, O[vt], 0, 0, 0);
;         }
;       }
;     __syncthreads();
;     if (j + 1 < nch) sstore();
;     __syncthreads();
.Lfa_keep:
	v_fma_f32 v96, v96, s35, -v14
	v_fma_f32 v97, v97, s35, -v14
	v_fma_f32 v98, v98, s35, -v14
	v_fma_f32 v99, v99, s35, -v14
	v_fma_f32 v100, v100, s35, -v14
	v_fma_f32 v101, v101, s35, -v14
	v_fma_f32 v102, v102, s35, -v14
	v_fma_f32 v103, v103, s35, -v14
	v_exp_f32_e32 v96, v96
	v_exp_f32_e32 v97, v97
	v_exp_f32_e32 v98, v98
	v_exp_f32_e32 v99, v99
	v_exp_f32_e32 v100, v100
	v_exp_f32_e32 v101, v101
	v_exp_f32_e32 v102, v102
	v_exp_f32_e32 v103, v103
	v_add_f32_e32 v15, v96, v98
	v_add_f32_e32 v205, v97, v99
	v_add_f32_e32 v15, v15, v100
	v_add_f32_e32 v205, v205, v101
	v_add_f32_e32 v15, v15, v102
	v_add_f32_e32 v205, v205, v103
	v_cvt_pk_bf16_f32 v96, v96, v97
	v_cvt_pk_bf16_f32 v97, v98, v99
	v_cvt_pk_bf16_f32 v98, v100, v101
	v_cvt_pk_bf16_f32 v99, v102, v103
	v_fma_f32 v104, v104, s35, -v14
	v_fma_f32 v105, v105, s35, -v14
	s_waitcnt lgkmcnt(2)
	v_mfma_f32_32x32x16_bf16 v[64:79], v[2:5], v[96:99], v[64:79]
	ds_read2_b64 v[2:5], v173 offset0:68 offset1:70
	v_fma_f32 v106, v106, s35, -v14
	v_fma_f32 v107, v107, s35, -v14
	v_fma_f32 v108, v108, s35, -v14
	v_fma_f32 v109, v109, s35, -v14
	v_fma_f32 v110, v110, s35, -v14
	v_fma_f32 v111, v111, s35, -v14
	v_exp_f32_e32 v104, v104
	s_waitcnt lgkmcnt(2)
	v_mfma_f32_32x32x16_bf16 v[48:63], v[6:9], v[96:99], v[48:63]
	ds_read2_b64 v[6:9], v188 offset0:132 offset1:134
	v_exp_f32_e32 v105, v105
	v_exp_f32_e32 v106, v106
	v_exp_f32_e32 v107, v107
	v_exp_f32_e32 v108, v108
	v_exp_f32_e32 v109, v109
	v_exp_f32_e32 v110, v110
	v_exp_f32_e32 v111, v111
	s_waitcnt lgkmcnt(2)
	v_mfma_f32_32x32x16_bf16 v[32:47], v[10:13], v[96:99], v[32:47]
	ds_read2_b64 v[10:13], v208 offset0:196 offset1:198
	v_add_f32_e32 v15, v15, v104
	v_add_f32_e32 v205, v205, v105
	v_add_f32_e32 v15, v15, v106
	v_add_f32_e32 v205, v205, v107
	v_add_f32_e32 v15, v15, v108
	v_add_f32_e32 v205, v205, v109
	v_add_f32_e32 v15, v15, v110
	s_waitcnt lgkmcnt(7)
	v_mfma_f32_32x32x16_bf16 v[16:31], v[222:225], v[96:99], v[16:31]
	ds_read2_b64 v[222:225], v161 offset0:8 offset1:10
	v_add_f32_e32 v205, v205, v111
	v_cvt_pk_bf16_f32 v104, v104, v105
	v_cvt_pk_bf16_f32 v105, v106, v107
	v_cvt_pk_bf16_f32 v106, v108, v109
	v_cvt_pk_bf16_f32 v107, v110, v111
	v_fma_f32 v80, v80, s35, -v14
	v_fma_f32 v81, v81, s35, -v14
	s_waitcnt lgkmcnt(7)
	v_mfma_f32_32x32x16_bf16 v[64:79], v[226:229], v[104:107], v[64:79]
	ds_read2_b64 v[226:229], v173 offset0:72 offset1:74
	v_fma_f32 v82, v82, s35, -v14
	v_fma_f32 v83, v83, s35, -v14
	v_fma_f32 v84, v84, s35, -v14
	v_fma_f32 v85, v85, s35, -v14
	v_fma_f32 v86, v86, s35, -v14
	v_fma_f32 v87, v87, s35, -v14
	v_exp_f32_e32 v80, v80
	s_waitcnt lgkmcnt(4)
	v_mfma_f32_32x32x16_bf16 v[48:63], v[2:5], v[104:107], v[48:63]
	ds_read2_b64 v[2:5], v188 offset0:136 offset1:138
	v_exp_f32_e32 v81, v81
	v_exp_f32_e32 v82, v82
	v_exp_f32_e32 v83, v83
	v_exp_f32_e32 v84, v84
	v_exp_f32_e32 v85, v85
	v_exp_f32_e32 v86, v86
	v_exp_f32_e32 v87, v87
	s_waitcnt lgkmcnt(4)
	v_mfma_f32_32x32x16_bf16 v[32:47], v[6:9], v[104:107], v[32:47]
	ds_read2_b64 v[6:9], v208 offset0:200 offset1:202
	v_add_f32_e32 v15, v15, v80
	v_add_f32_e32 v205, v205, v81
	v_add_f32_e32 v15, v15, v82
	v_add_f32_e32 v205, v205, v83
	v_add_f32_e32 v15, v15, v84
	v_add_f32_e32 v205, v205, v85
	v_add_f32_e32 v15, v15, v86
	s_waitcnt lgkmcnt(4)
	v_mfma_f32_32x32x16_bf16 v[16:31], v[10:13], v[104:107], v[16:31]
	ds_read2_b64 v[10:13], v161 offset0:12 offset1:14
	v_add_f32_e32 v205, v205, v87
	v_cvt_pk_bf16_f32 v80, v80, v81
	v_cvt_pk_bf16_f32 v81, v82, v83
	v_cvt_pk_bf16_f32 v82, v84, v85
	v_cvt_pk_bf16_f32 v83, v86, v87
	v_fma_f32 v88, v88, s35, -v14
	v_fma_f32 v89, v89, s35, -v14
	s_waitcnt lgkmcnt(4)
	v_mfma_f32_32x32x16_bf16 v[64:79], v[222:225], v[80:83], v[64:79]
	ds_read2_b64 v[222:225], v173 offset0:76 offset1:78
	v_fma_f32 v90, v90, s35, -v14
	v_fma_f32 v91, v91, s35, -v14
	v_fma_f32 v92, v92, s35, -v14
	v_fma_f32 v93, v93, s35, -v14
	v_fma_f32 v94, v94, s35, -v14
	v_fma_f32 v95, v95, s35, -v14
	v_exp_f32_e32 v88, v88
	s_waitcnt lgkmcnt(4)
	v_mfma_f32_32x32x16_bf16 v[48:63], v[226:229], v[80:83], v[48:63]
	ds_read2_b64 v[226:229], v188 offset0:140 offset1:142
	v_exp_f32_e32 v89, v89
	v_exp_f32_e32 v90, v90
	v_exp_f32_e32 v91, v91
	v_exp_f32_e32 v92, v92
	v_exp_f32_e32 v93, v93
	v_exp_f32_e32 v94, v94
	v_exp_f32_e32 v95, v95
	s_waitcnt lgkmcnt(4)
	v_mfma_f32_32x32x16_bf16 v[32:47], v[2:5], v[80:83], v[32:47]
	ds_read2_b64 v[2:5], v208 offset0:204 offset1:206
	v_add_f32_e32 v15, v15, v88
	v_add_f32_e32 v205, v205, v89
	v_add_f32_e32 v15, v15, v90
	v_add_f32_e32 v205, v205, v91
	v_add_f32_e32 v15, v15, v92
	v_add_f32_e32 v205, v205, v93
	v_add_f32_e32 v15, v15, v94
	s_waitcnt lgkmcnt(4)
	v_mfma_f32_32x32x16_bf16 v[16:31], v[6:9], v[80:83], v[16:31]
	v_add_f32_e32 v205, v205, v95
	v_cvt_pk_bf16_f32 v88, v88, v89
	v_cvt_pk_bf16_f32 v89, v90, v91
	v_cvt_pk_bf16_f32 v90, v92, v93
	v_cvt_pk_bf16_f32 v91, v94, v95
	s_waitcnt lgkmcnt(0)
	s_barrier
	s_nop 1
	v_mfma_f32_32x32x16_bf16 v[64:79], v[10:13], v[88:91], v[64:79]
	s_waitcnt vmcnt(7)
	ds_write_b128 v180, v[128:131]
	s_waitcnt vmcnt(6)
	ds_write_b128 v180, v[132:135] offset:18432
	v_mfma_f32_32x32x16_bf16 v[48:63], v[222:225], v[88:91], v[48:63]
	s_waitcnt vmcnt(5)
	ds_write_b128 v182, v[136:139]
	s_waitcnt vmcnt(4)
	ds_write_b128 v182, v[140:143] offset:18432
	v_mfma_f32_32x32x16_bf16 v[32:47], v[226:229], v[88:91], v[32:47]
	s_waitcnt vmcnt(3)
	ds_write_b128 v184, v[144:147]
	s_waitcnt vmcnt(2)
	ds_write_b128 v184, v[148:151] offset:18432
	v_mfma_f32_32x32x16_bf16 v[16:31], v[2:5], v[88:91], v[16:31]
	s_waitcnt vmcnt(1)
	ds_write_b128 v186, v[152:155]
	s_waitcnt vmcnt(0)
	ds_write_b128 v186, v[156:159] offset:18432
	v_add_f32_e32 v15, v15, v205
	s_add_u32 s36, s36, 0x80
	s_addc_u32 s37, s37, 0
	s_add_i32 s38, s38, 64
	s_add_i32 s92, s92, 64
	v_fma_f32 v203, v203, v0, v15
	v_add_u32_e32 v199, 64, v199
	s_mov_b32 s39, s93
	s_waitcnt lgkmcnt(0)
	s_barrier
	s_branch .LBB0_591
